# v8 + NA attention loop bound: 11 key-row tiles per unit instead of 12 (8 for the first query block) - the dropped tiles were outside every wave's window; bit-identical
# baseline (speedup 1.0000x reference)
; #define ALAS __attribute__((address_space(3)))
; __device__ __forceinline__ void attn_body3n(const AGAS bf16* __restrict__ Qb, const AGAS bf16* __restrict__ Kh, const AGAS bf16* __restrict__ V0h, AGAS bf16* __restrict__ Ob, int ldo, int NT, Mod M, ALAS char* lds) {
;   int tid_o = threadIdx.x; asm volatile("" : "+v"(tid_o));
;   const int tid = tid_o, wid = __builtin_amdgcn_readfirstlane(tid >> 6), lane = tid & 63, r32 = lane & 31, hi = lane >> 5;
;   ALAS float* ws = (ALAS float*)(lds + B3_WS) + wid * 64; ALAS float* li_l = ws; ALAS float* al_l = ws + 32;
;   float m_reg = -1e30f, l_reg = 0; f32x16 o0[4] = {}; bf16x8 qr[8];
;   const AGAS bf16* Qw = Qb + (long)(wid * QBLK + r32) * LDQ + hi * 8;
; #pragma unroll
; template <int ch>
; __device__ __forceinline__ void chunk_body(const Args& a, LAS unsigned char* lds, const XcdBarrier& bar, const int G, const int bx, const int vcu, const int gw, const int NGW, const int tid, const int lane, const int wave) {
;     ...
;             for (int u = vcu; u < n_na; u += G) {
;                 const int combo = u / nqb, qb = u % nqb, sq = combo >> 3, h = combo & 7;
;                 const size_t tok0 = (size_t)sq * slen;
;                 const int r0 = qb * 4; int kr0 = r0 - 4; kr0 = kr0 < 0 ? 0 : (kr0 > R - 8 ? R - 8 : kr0);
;                 const int NT = (R - kr0) < 12 ? (R - kr0) : 12;
;                 __syncthreads();
;                 for (int i = tid; i < 465; i += NWAVES * 64) tab[i] = ((const GAS float*)a.rpb)[h * 465 + i] * (1.0f / att::SCALE);
;                 const GAS bf16* Q = (const GAS bf16*)SEG + ((size_t)(24 + h) * TC + tok0 + qb * 256) * 128;
;                 const GAS bf16* K = (const GAS bf16*)SEG + ((size_t)(32 + h) * TC + tok0 + kr0 * 64) * 128;
;                 const GAS bf16* V = (const GAS bf16*)SEG + ((size_t)(40 + h) * TC + tok0 + kr0 * 64) * 128;
;                 GAS bf16* O = (GAS bf16*)ON + (tok0 + qb * 256) * DM + h * 128;
;                 att::Mod M; M.a0 = 0.f; M.a1 = 0.f; M.jd = 0; M.cen = 0; M.rq = r0 + (wave >> 1); { int t = M.rq - 4; M.rsq = t < 0 ? 0 : (t > R - 8 ? R - 8 : t); }
;                 M.kr0 = kr0; M.c = (wave & 1) * 32 + r32; { int t = M.c - 8; M.cs = t < 0 ? 0 : (t > 48 ? 48 : t); } M.hi = hi; M.tab = tab;
;                 M.tab = (const LAS float*)(lds + att::B3_WS + 2048);
;                 att::attn_body3n(Q, K, V, O, DM, NT, M, (LAS char*)lds);
.LBB0_378:
	s_min_u32 s83, s8, 11
	s_cmp_eq_u32 s88, 0
	s_cselect_b32 s83, 8, s83
	s_and_b32 s8, s14, 0x3fffffc0
	s_lshl_b32 s8, s8, 2
	s_add_i32 s82, s8, 0
	s_add_i32 s88, s88, s72
	s_add_i32 s82, s82, 0x18000
	s_add_u32 s84, s53, s4
	s_addc_u32 s85, s55, s5
	s_lshl_b32 s4, s7, 10
	s_add_i32 m0, s18, s4
	v_lshlrev_b32_e32 v13, 4, v2
	global_load_lds_dwordx4 v19, s[84:85]
	s_lshl_b32 s7, s15, 2
	v_lshlrev_b32_e32 v17, 1, v2
	v_and_b32_e32 v13, 0xc0, v13
	v_and_b32_e32 v3, 0x100, v3
	v_cmp_gt_u32_e64 s[4:5], 32, v2
	v_or3_b32 v2, s7, v5, v1
	v_lshl_or_b32 v5, v6, 4, v7
	v_and_or_b32 v6, v8, 51, v1
	v_and_or_b32 v1, v14, 51, v1
	v_med3_i32 v12, s88, 4, 60
	v_and_b32_e32 v17, 32, v17
	v_lshl_or_b32 v2, v2, 8, v4
	v_lshlrev_b32_e32 v1, 8, v1
	v_lshl_or_b32 v145, v15, 4, v16
	v_or3_b32 v0, v13, v3, v0
	v_mov_b32_e32 v14, v129
	v_mov_b32_e32 v15, v129
	v_add_u32_e32 v139, -4, v12
	v_add_u32_e32 v141, 4, v12
	v_lshl_or_b32 v142, v6, 8, v9
	v_lshl_or_b32 v143, v10, 4, v11
	v_or3_b32 v144, v1, v4, s42
	v_cndmask_b32_e64 v128, v2, v5, s[0:1]
	v_add3_u32 v146, v17, 0, v0
	v_mov_b32_e32 v0, v129
	v_mov_b32_e32 v1, v129
	v_mov_b32_e32 v2, v129
	v_mov_b32_e32 v3, v129
	v_mov_b32_e32 v4, v129
	v_mov_b32_e32 v5, v129
	v_mov_b32_e32 v6, v129
	v_mov_b32_e32 v7, v129
	v_mov_b32_e32 v8, v129
	v_mov_b32_e32 v9, v129
	v_mov_b32_e32 v10, v129
	v_mov_b32_e32 v11, v129
	v_mov_b32_e32 v12, v129
	v_mov_b32_e32 v13, v129
	v_mov_b64_e32 v[62:63], v[14:15]
	v_mov_b64_e32 v[46:47], v[14:15]
	v_mov_b64_e32 v[30:31], v[14:15]
	v_lshl_add_u32 v140, v136, 2, s82
	s_lshl_b32 s89, s6, 10
	s_mov_b32 s16, 0
	v_mov_b32_e32 v148, 0
	v_mov_b32_e32 v147, 0xf149f2ca
	v_mov_b64_e32 v[60:61], v[12:13]
	v_mov_b64_e32 v[58:59], v[10:11]
	v_mov_b64_e32 v[56:57], v[8:9]
	v_mov_b64_e32 v[54:55], v[6:7]
	v_mov_b64_e32 v[52:53], v[4:5]
	v_mov_b64_e32 v[50:51], v[2:3]
	v_mov_b64_e32 v[48:49], v[0:1]
	v_mov_b64_e32 v[44:45], v[12:13]
	v_mov_b64_e32 v[42:43], v[10:11]
	v_mov_b64_e32 v[40:41], v[8:9]
	v_mov_b64_e32 v[38:39], v[6:7]
	v_mov_b64_e32 v[36:37], v[4:5]
	v_mov_b64_e32 v[34:35], v[2:3]
	v_mov_b64_e32 v[32:33], v[0:1]
	v_mov_b64_e32 v[28:29], v[12:13]
	v_mov_b64_e32 v[26:27], v[10:11]
	v_mov_b64_e32 v[24:25], v[8:9]
	v_mov_b64_e32 v[22:23], v[6:7]
	v_mov_b64_e32 v[20:21], v[4:5]
	v_mov_b64_e32 v[18:19], v[2:3]
	v_mov_b64_e32 v[16:17], v[0:1]
	s_waitcnt vmcnt(0)

; #define ALAS __attribute__((address_space(3)))
; __device__ __forceinline__ void attn_body3n(const AGAS bf16* __restrict__ Qb, const AGAS bf16* __restrict__ Kh, const AGAS bf16* __restrict__ V0h, AGAS bf16* __restrict__ Ob, int ldo, int NT, Mod M, ALAS char* lds) {
;   int tid_o = threadIdx.x; asm volatile("" : "+v"(tid_o));
;   const int tid = tid_o, wid = __builtin_amdgcn_readfirstlane(tid >> 6), lane = tid & 63, r32 = lane & 31, hi = lane >> 5;
;   ALAS float* ws = (ALAS float*)(lds + B3_WS) + wid * 64; ALAS float* li_l = ws; ALAS float* al_l = ws + 32;
;   float m_reg = -1e30f, l_reg = 0; f32x16 o0[4] = {}; bf16x8 qr[8];
;   const AGAS bf16* Qw = Qb + (long)(wid * QBLK + r32) * LDQ + hi * 8;
; #pragma unroll
; template <int ch>
; __device__ __forceinline__ void chunk_body(const Args& a, LAS unsigned char* lds, const XcdBarrier& bar, const int G, const int bx, const int vcu, const int gw, const int NGW, const int tid, const int lane, const int wave) {
;     ...
;             for (int u = vcu; u < n_na; u += G) {
;                 const int combo = u / nqb, qb = u % nqb, sq = combo >> 3, h = combo & 7;
;                 const size_t tok0 = (size_t)sq * slen;
;                 const int r0 = qb * 4; int kr0 = r0 - 4; kr0 = kr0 < 0 ? 0 : (kr0 > R - 8 ? R - 8 : kr0);
;                 const int NT = (R - kr0) < 12 ? (R - kr0) : 12;
;                 __syncthreads();
;                 for (int i = tid; i < 465; i += NWAVES * 64) tab[i] = ((const GAS float*)a.rpb)[h * 465 + i] * (1.0f / att::SCALE);
;                 const GAS bf16* Q = (const GAS bf16*)SEG + ((size_t)(24 + h) * TC + tok0 + qb * 256) * 128;
;                 const GAS bf16* K = (const GAS bf16*)SEG + ((size_t)(32 + h) * TC + tok0 + kr0 * 64) * 128;
;                 const GAS bf16* V = (const GAS bf16*)SEG + ((size_t)(40 + h) * TC + tok0 + kr0 * 64) * 128;
;                 GAS bf16* O = (GAS bf16*)ON + (tok0 + qb * 256) * DM + h * 128;
;                 att::Mod M; M.a0 = 0.f; M.a1 = 0.f; M.jd = 0; M.cen = 0; M.rq = r0 + (wave >> 1); { int t = M.rq - 4; M.rsq = t < 0 ? 0 : (t > R - 8 ? R - 8 : t); }
;                 M.kr0 = kr0; M.c = (wave & 1) * 32 + r32; { int t = M.c - 8; M.cs = t < 0 ? 0 : (t > 48 ? 48 : t); } M.hi = hi; M.tab = tab;
;                 M.tab = (const LAS float*)(lds + att::B3_WS + 2048);
;                 att::attn_body3n(Q, K, V, O, DM, NT, M, (LAS char*)lds);
.LBB0_1034:
	s_min_u32 s83, s14, 11
	s_cmp_eq_u32 s86, 0
	s_cselect_b32 s83, 8, s83
	s_and_b32 s14, s18, 0x3fffffc0
	s_lshl_b32 s14, s14, 2
	s_add_i32 s82, s14, 0
	s_add_i32 s86, s86, s72
	s_add_i32 s82, s82, 0x18000
	s_add_u32 s80, s53, s8
	s_addc_u32 s81, s55, s9
	s_lshl_b32 s8, s13, 10
	s_add_i32 m0, s22, s8
	v_lshlrev_b32_e32 v13, 4, v2
	global_load_lds_dwordx4 v19, s[80:81]
	s_lshl_b32 s13, s19, 2
	v_lshlrev_b32_e32 v17, 1, v2
	v_and_b32_e32 v13, 0xc0, v13
	v_and_b32_e32 v3, 0x100, v3
	v_cmp_gt_u32_e64 s[8:9], 32, v2
	v_or3_b32 v2, s13, v5, v1
	v_lshl_or_b32 v5, v6, 4, v7
	v_and_or_b32 v6, v8, 51, v1
	v_and_or_b32 v1, v14, 51, v1
	v_med3_i32 v12, s86, 4, 28
	v_and_b32_e32 v17, 32, v17
	v_lshl_or_b32 v2, v2, 8, v4
	v_lshlrev_b32_e32 v1, 8, v1
	v_lshl_or_b32 v145, v15, 4, v16
	v_or3_b32 v0, v13, v3, v0
	v_mov_b32_e32 v14, v129
	v_mov_b32_e32 v15, v129
	v_add_u32_e32 v139, -4, v12
	v_add_u32_e32 v141, 4, v12
	v_lshl_or_b32 v142, v6, 8, v9
	v_lshl_or_b32 v143, v10, 4, v11
	v_or3_b32 v144, v1, v4, s11
	v_cndmask_b32_e64 v128, v2, v5, s[0:1]
	v_add3_u32 v146, v17, 0, v0
	v_mov_b32_e32 v0, v129
	v_mov_b32_e32 v1, v129
	v_mov_b32_e32 v2, v129
	v_mov_b32_e32 v3, v129
	v_mov_b32_e32 v4, v129
	v_mov_b32_e32 v5, v129
	v_mov_b32_e32 v6, v129
	v_mov_b32_e32 v7, v129
	v_mov_b32_e32 v8, v129
	v_mov_b32_e32 v9, v129
	v_mov_b32_e32 v10, v129
	v_mov_b32_e32 v11, v129
	v_mov_b32_e32 v12, v129
	v_mov_b32_e32 v13, v129
	v_mov_b64_e32 v[62:63], v[14:15]
	v_mov_b64_e32 v[46:47], v[14:15]
	v_mov_b64_e32 v[30:31], v[14:15]
	v_lshl_add_u32 v140, v136, 2, s82
	s_lshl_b32 s87, s12, 10
	s_mov_b32 s20, 0
	v_mov_b32_e32 v148, 0
	v_mov_b32_e32 v147, 0xf149f2ca
	v_mov_b64_e32 v[60:61], v[12:13]
	v_mov_b64_e32 v[58:59], v[10:11]
	v_mov_b64_e32 v[56:57], v[8:9]
	v_mov_b64_e32 v[54:55], v[6:7]
	v_mov_b64_e32 v[52:53], v[4:5]
	v_mov_b64_e32 v[50:51], v[2:3]
	v_mov_b64_e32 v[48:49], v[0:1]
	v_mov_b64_e32 v[44:45], v[12:13]
	v_mov_b64_e32 v[42:43], v[10:11]
	v_mov_b64_e32 v[40:41], v[8:9]
	v_mov_b64_e32 v[38:39], v[6:7]
	v_mov_b64_e32 v[36:37], v[4:5]
	v_mov_b64_e32 v[34:35], v[2:3]
	v_mov_b64_e32 v[32:33], v[0:1]
	v_mov_b64_e32 v[28:29], v[12:13]
	v_mov_b64_e32 v[26:27], v[10:11]
	v_mov_b64_e32 v[24:25], v[8:9]
	v_mov_b64_e32 v[22:23], v[6:7]
	v_mov_b64_e32 v[20:21], v[4:5]
	v_mov_b64_e32 v[18:19], v[2:3]
	v_mov_b64_e32 v[16:17], v[0:1]
	s_waitcnt vmcnt(0)

; #define ALAS __attribute__((address_space(3)))
; __device__ __forceinline__ void attn_body3n(const AGAS bf16* __restrict__ Qb, const AGAS bf16* __restrict__ Kh, const AGAS bf16* __restrict__ V0h, AGAS bf16* __restrict__ Ob, int ldo, int NT, Mod M, ALAS char* lds) {
;   int tid_o = threadIdx.x; asm volatile("" : "+v"(tid_o));
;   const int tid = tid_o, wid = __builtin_amdgcn_readfirstlane(tid >> 6), lane = tid & 63, r32 = lane & 31, hi = lane >> 5;
;   ALAS float* ws = (ALAS float*)(lds + B3_WS) + wid * 64; ALAS float* li_l = ws; ALAS float* al_l = ws + 32;
;   float m_reg = -1e30f, l_reg = 0; f32x16 o0[4] = {}; bf16x8 qr[8];
;   const AGAS bf16* Qw = Qb + (long)(wid * QBLK + r32) * LDQ + hi * 8;
; #pragma unroll
; template <int ch>
; __device__ __forceinline__ void chunk_body(const Args& a, LAS unsigned char* lds, const XcdBarrier& bar, const int G, const int bx, const int vcu, const int gw, const int NGW, const int tid, const int lane, const int wave) {
;     ...
;             for (int u = vcu; u < n_na; u += G) {
;                 const int combo = u / nqb, qb = u % nqb, sq = combo >> 3, h = combo & 7;
;                 const size_t tok0 = (size_t)sq * slen;
;                 const int r0 = qb * 4; int kr0 = r0 - 4; kr0 = kr0 < 0 ? 0 : (kr0 > R - 8 ? R - 8 : kr0);
;                 const int NT = (R - kr0) < 12 ? (R - kr0) : 12;
;                 __syncthreads();
;                 for (int i = tid; i < 465; i += NWAVES * 64) tab[i] = ((const GAS float*)a.rpb)[h * 465 + i] * (1.0f / att::SCALE);
;                 const GAS bf16* Q = (const GAS bf16*)SEG + ((size_t)(24 + h) * TC + tok0 + qb * 256) * 128;
;                 const GAS bf16* K = (const GAS bf16*)SEG + ((size_t)(32 + h) * TC + tok0 + kr0 * 64) * 128;
;                 const GAS bf16* V = (const GAS bf16*)SEG + ((size_t)(40 + h) * TC + tok0 + kr0 * 64) * 128;
;                 GAS bf16* O = (GAS bf16*)ON + (tok0 + qb * 256) * DM + h * 128;
;                 att::Mod M; M.a0 = 0.f; M.a1 = 0.f; M.jd = 0; M.cen = 0; M.rq = r0 + (wave >> 1); { int t = M.rq - 4; M.rsq = t < 0 ? 0 : (t > R - 8 ? R - 8 : t); }
;                 M.kr0 = kr0; M.c = (wave & 1) * 32 + r32; { int t = M.c - 8; M.cs = t < 0 ? 0 : (t > 48 ? 48 : t); } M.hi = hi; M.tab = tab;
;                 M.tab = (const LAS float*)(lds + att::B3_WS + 2048);
;                 att::attn_body3n(Q, K, V, O, DM, NT, M, (LAS char*)lds);
.LBB0_1690:
	s_min_u32 s70, s8, 11
	s_cmp_eq_u32 s71, 0
	s_cselect_b32 s70, 8, s70
	s_and_b32 s8, s14, 0x3fffffc0
	s_lshl_b32 s8, s8, 2
	s_add_i32 s69, s8, 0
	s_add_i32 s71, s71, s75
	s_add_i32 s69, s69, 0x18000
	s_add_u32 s62, s53, s4
	s_addc_u32 s63, s55, s5
	s_lshl_b32 s4, s7, 10
	s_add_i32 m0, s18, s4
	v_lshlrev_b32_e32 v13, 4, v2
	global_load_lds_dwordx4 v19, s[62:63]
	s_lshl_b32 s7, s15, 2
	v_lshlrev_b32_e32 v17, 1, v2
	v_and_b32_e32 v13, 0xc0, v13
	v_and_b32_e32 v3, 0x100, v3
	v_cmp_gt_u32_e64 s[4:5], 32, v2
	v_or3_b32 v2, s7, v5, v1
	v_lshl_or_b32 v5, v6, 4, v7
	v_and_or_b32 v6, v8, 51, v1
	v_and_or_b32 v1, v14, 51, v1
	v_med3_i32 v12, s71, 4, 28
	v_and_b32_e32 v17, 32, v17
	v_lshl_or_b32 v2, v2, 8, v4
	v_lshlrev_b32_e32 v1, 8, v1
	v_lshl_or_b32 v145, v15, 4, v16
	v_or3_b32 v0, v13, v3, v0
	v_mov_b32_e32 v14, v129
	v_mov_b32_e32 v15, v129
	v_add_u32_e32 v139, -4, v12
	v_add_u32_e32 v141, 4, v12
	v_lshl_or_b32 v142, v6, 8, v9
	v_lshl_or_b32 v143, v10, 4, v11
	v_or3_b32 v144, v1, v4, s44
	v_cndmask_b32_e64 v128, v2, v5, s[0:1]
	v_add3_u32 v146, v17, 0, v0
	v_mov_b32_e32 v0, v129
	v_mov_b32_e32 v1, v129
	v_mov_b32_e32 v2, v129
	v_mov_b32_e32 v3, v129
	v_mov_b32_e32 v4, v129
	v_mov_b32_e32 v5, v129
	v_mov_b32_e32 v6, v129
	v_mov_b32_e32 v7, v129
	v_mov_b32_e32 v8, v129
	v_mov_b32_e32 v9, v129
	v_mov_b32_e32 v10, v129
	v_mov_b32_e32 v11, v129
	v_mov_b32_e32 v12, v129
	v_mov_b32_e32 v13, v129
	v_mov_b64_e32 v[62:63], v[14:15]
	v_mov_b64_e32 v[46:47], v[14:15]
	v_mov_b64_e32 v[30:31], v[14:15]
	v_lshl_add_u32 v140, v136, 2, s69
	s_lshl_b32 s72, s6, 10
	s_mov_b32 s16, 0
	v_mov_b32_e32 v147, 0
	v_mov_b32_e32 v148, 0xf149f2ca
	v_mov_b64_e32 v[60:61], v[12:13]
	v_mov_b64_e32 v[58:59], v[10:11]
	v_mov_b64_e32 v[56:57], v[8:9]
	v_mov_b64_e32 v[54:55], v[6:7]
	v_mov_b64_e32 v[52:53], v[4:5]
	v_mov_b64_e32 v[50:51], v[2:3]
	v_mov_b64_e32 v[48:49], v[0:1]
	v_mov_b64_e32 v[44:45], v[12:13]
	v_mov_b64_e32 v[42:43], v[10:11]
	v_mov_b64_e32 v[40:41], v[8:9]
	v_mov_b64_e32 v[38:39], v[6:7]
	v_mov_b64_e32 v[36:37], v[4:5]
	v_mov_b64_e32 v[34:35], v[2:3]
	v_mov_b64_e32 v[32:33], v[0:1]
	v_mov_b64_e32 v[28:29], v[12:13]
	v_mov_b64_e32 v[26:27], v[10:11]
	v_mov_b64_e32 v[24:25], v[8:9]
	v_mov_b64_e32 v[22:23], v[6:7]
	v_mov_b64_e32 v[20:21], v[4:5]
	v_mov_b64_e32 v[18:19], v[2:3]
	v_mov_b64_e32 v[16:17], v[0:1]
	s_waitcnt vmcnt(0)
